# P0 rmsnorm row loop: two rows in flight per wave instead of one (loop unrolled by two with alternating prefetch buffers, exact counted vmcnt)
# baseline (speedup 1.0000x reference)
; #define LAS __attribute__((address_space(3)))
; __global__ void __launch_bounds__(NWAVES * 64, 2) mk_fwd(Args args) {
;     ...
;         for (int i = tid; i < 8192; i += NWAVES * 64) { const int k = i >> 3, h = i & 7; wfT[h * 1024 + k] = w_in[(size_t)k * DIN + 2560 + h]; }
;         __syncthreads();
;         f32x4 wfr[8][4];
; #pragma unroll
;         for (int h = 0; h < 8; ++h)
; #pragma unroll
;             for (int j = 0; j < 4; ++j) wfr[h][j] = *(const LAS f32x4*)(wfT + h * 1024 + 256 * j + 4 * lane);
;         f32x4 gg[4];
; #pragma unroll
;         for (int j = 0; j < 4; ++j) gg[j] = ((const f32x4*)g_mix)[64 * j + lane];
;         const int hsel = ((lane >> 5) & 1) * 4 + ((lane >> 4) & 1) * 2 + ((lane >> 3) & 1);
;         const float bfl = b_f[hsel];
;         {
;             f32x4 cur[4], nxt[4];
;             int m = gw;
;             if (m < T) { const f32x4* xr = (const f32x4*)(x + (size_t)m * DM) + lane;
; #pragma unroll
;                 for (int j = 0; j < 4; ++j) cur[j] = xr[64 * j]; }
; #pragma unroll 1
;             for (; m < T; m += NGW) {
;                 const int mn = m + NGW;
;                 if (mn < T) { const f32x4* xr = (const f32x4*)(x + (size_t)mn * DM) + lane;
; #pragma unroll
;                     for (int j = 0; j < 4; ++j) nxt[j] = xr[64 * j]; }
.LBB0_34:
	s_or_b64 exec, exec, s[10:11]
	s_cmp_lt_i32 s14, 0x8000
	v_mov_b32_e32 v19, 0
	s_waitcnt lgkmcnt(0)
	s_barrier
	s_cbranch_scc0 .LBB0_41
	v_mov_b32_e32 v177, v19
	s_ashr_i32 s15, s14, 31
	v_lshl_add_u64 v[22:23], s[4:5], 0, v[176:177]
	s_lshl_b64 s[4:5], s[14:15], 12
	v_lshrrev_b32_e32 v0, 1, v17
	s_add_u32 s4, s12, s4
	v_and_b32_e32 v18, 28, v0
	s_addc_u32 s5, s13, s5
	v_lshl_add_u64 v[0:1], s[6:7], 0, v[18:19]
	v_lshl_add_u32 v140, v20, 4, 0
	v_lshl_add_u64 v[20:21], s[4:5], 0, v[176:177]
	flat_load_dword v190, v[0:1]
	s_nop 0
	flat_load_dwordx4 v[0:3], v[22:23] offset:3072
	flat_load_dwordx4 v[4:7], v[22:23] offset:2048
	flat_load_dwordx4 v[8:11], v[22:23] offset:1024
	flat_load_dwordx4 v[12:15], v[22:23]
	flat_load_dwordx4 v[172:175], v[20:21]
	flat_load_dwordx4 v[168:171], v[20:21] offset:1024
	flat_load_dwordx4 v[164:167], v[20:21] offset:2048
	flat_load_dwordx4 v[160:163], v[20:21] offset:3072
	v_mbcnt_lo_u32_b32 v20, -1, 0
	v_mbcnt_hi_u32_b32 v20, -1, v20
	v_and_b32_e32 v21, 64, v20
	v_add_u32_e32 v21, 64, v21
	v_xor_b32_e32 v22, 1, v20
	v_cmp_lt_i32_e32 vcc, v22, v21
	s_lshl_b64 s[28:29], s[14:15], 5
	s_add_u32 s26, s26, s28
	v_cndmask_b32_e32 v22, v20, v22, vcc
	v_lshlrev_b32_e32 v191, 2, v22
	v_xor_b32_e32 v22, 2, v20
	v_cmp_lt_i32_e32 vcc, v22, v21
	s_addc_u32 s27, s27, s29
	v_cmp_eq_u32_e64 s[10:11], 0, v16
	v_cndmask_b32_e32 v22, v20, v22, vcc
	v_lshlrev_b32_e32 v192, 2, v22
	v_xor_b32_e32 v22, 4, v20
	v_cmp_lt_i32_e32 vcc, v22, v21
	s_ashr_i32 s39, s38, 31
	s_lshl_b64 s[28:29], s[14:15], 11
	v_cndmask_b32_e32 v22, v20, v22, vcc
	v_lshlrev_b32_e32 v193, 2, v22
	v_xor_b32_e32 v22, 8, v20
	v_cmp_lt_i32_e32 vcc, v22, v21
	v_mov_b32_e32 v179, v19
	s_mov_b32 s3, 0xf800000
	v_cndmask_b32_e32 v22, v20, v22, vcc
	v_lshlrev_b32_e32 v194, 2, v22
	v_xor_b32_e32 v22, 16, v20
	v_cmp_lt_i32_e32 vcc, v22, v21
	s_mov_b32 s15, 0xbfb8aa3b
	s_mov_b32 s33, 0xb2a5705f
	v_cndmask_b32_e32 v22, v20, v22, vcc
	v_lshlrev_b32_e32 v195, 2, v22
	v_xor_b32_e32 v22, 32, v20
	v_cmp_lt_i32_e32 vcc, v22, v21
	s_mov_b32 s34, 0x42ce8ed0
	s_mov_b32 s35, 0xc2b17218
	v_cndmask_b32_e32 v20, v20, v22, vcc
	v_lshlrev_b32_e32 v196, 2, v20
	v_and_b32_e32 v20, 32, v17
	v_cmp_eq_u32_e64 s[4:5], 0, v20
	v_and_b32_e32 v20, 16, v17
	v_and_b32_e32 v17, 8, v17
	v_cmp_eq_u32_e64 s[8:9], 0, v17
	v_lshl_add_u64 v[16:17], s[26:27], 0, v[18:19]
	s_mov_b64 s[26:27], 0x2000000
	v_lshl_add_u64 v[180:181], v[16:17], 0, s[26:27]
	s_lshl_b64 s[26:27], s[38:39], 5
	s_add_u32 s22, s22, s28
	s_addc_u32 s23, s23, s29
	v_lshl_add_u64 v[16:17], s[22:23], 0, v[178:179]
	s_mov_b64 s[22:23], 0x4000000
	v_lshl_add_u64 v[182:183], v[16:17], 0, s[22:23]
	v_cmp_eq_u32_e64 s[6:7], 0, v20
	ds_read_b128 v[16:19], v140 offset:31744
	ds_read_b128 v[20:23], v140 offset:30720
	ds_read_b128 v[24:27], v140 offset:29696
	ds_read_b128 v[28:31], v140 offset:28672
	ds_read_b128 v[32:35], v140 offset:27648
	ds_read_b128 v[36:39], v140 offset:26624
	ds_read_b128 v[40:43], v140 offset:25600
	ds_read_b128 v[44:47], v140 offset:24576
	ds_read_b128 v[48:51], v140 offset:23552
	ds_read_b128 v[52:55], v140 offset:22528
	ds_read_b128 v[56:59], v140 offset:21504
	ds_read_b128 v[60:63], v140 offset:20480
	ds_read_b128 v[64:67], v140 offset:19456
	ds_read_b128 v[68:71], v140 offset:18432
	ds_read_b128 v[72:75], v140 offset:17408
	ds_read_b128 v[76:79], v140 offset:16384
	ds_read_b128 v[80:83], v140 offset:15360
	ds_read_b128 v[84:87], v140 offset:14336
	ds_read_b128 v[88:91], v140 offset:13312
	ds_read_b128 v[92:95], v140 offset:12288
	ds_read_b128 v[96:99], v140 offset:11264
	ds_read_b128 v[100:103], v140 offset:10240
	ds_read_b128 v[104:107], v140 offset:9216
	ds_read_b128 v[108:111], v140 offset:8192
	ds_read_b128 v[112:115], v140 offset:7168
	ds_read_b128 v[116:119], v140 offset:6144
	ds_read_b128 v[120:123], v140 offset:5120
	ds_read_b128 v[124:127], v140 offset:4096
	ds_read_b128 v[128:131], v140 offset:3072
	ds_read_b128 v[132:135], v140 offset:2048
	ds_read_b128 v[136:139], v140 offset:1024
	ds_read_b128 v[140:143], v140
	s_add_i32 s28, s14, s38
	s_ashr_i32 s29, s28, 31
	s_lshl_b64 s[22:23], s[38:39], 11
	s_lshl_b64 s[28:29], s[28:29], 12
	s_add_u32 s12, s12, s28
	s_addc_u32 s13, s13, s29
	v_lshl_add_u64 v[184:185], s[12:13], 0, v[176:177]
	s_lshl_b64 s[28:29], s[38:39], 12
	v_mov_b32_e32 v177, 0x358637bd
	v_mov_b32_e32 v179, 0x260
	s_mov_b32 s36, 0x7f800000
	s_mov_b32 s37, 0x3f2aaaab
	v_mov_b32_e32 v197, 0x3ecc95a3
	s_mov_b32 s39, 0x3f317218
	s_mov_b32 s42, 0x33800000
	v_mov_b32_e32 v198, 0x7f800000
	v_mov_b32_e32 v186, 0x3f317218
	s_mov_b32 s43, s14
	s_waitcnt vmcnt(0) lgkmcnt(0)
	s_add_i32 s98, s14, s38
	s_cmpk_gt_i32 s98, 0x7fff
	s_cbranch_scc1 .Lp0_nopre
	global_load_dwordx4 v[144:147], v[184:185], off
	global_load_dwordx4 v[148:151], v[184:185], off offset:1024
	global_load_dwordx4 v[152:155], v[184:185], off offset:2048
	global_load_dwordx4 v[156:159], v[184:185], off offset:3072

; __global__ void __launch_bounds__(NWAVES * 64, 2) mk_fwd(Args args) {
;     ...
;             for (; m < T; m += NGW) {
;                 const int mn = m + NGW;
;                 if (mn < T) { const f32x4* xr = (const f32x4*)(x + (size_t)mn * DM) + lane;
; #pragma unroll
;                     for (int j = 0; j < 4; ++j) nxt[j] = xr[64 * j]; }
;                 float s = 0.f;
; #pragma unroll
;                 for (int j = 0; j < 4; ++j) s += (cur[j][0] * cur[j][0] + cur[j][1] * cur[j][1]) + (cur[j][2] * cur[j][2] + cur[j][3] * cur[j][3]);
;                 float z[8];
; #pragma unroll
;                 for (int h = 0; h < 8; ++h) z[h] = 0.f;
; #pragma unroll
;                 for (int j = 0; j < 4; ++j) { cur[j] = cur[j] * gg[j];
; #pragma unroll
;                     for (int h = 0; h < 8; ++h) z[h] += (cur[j][0] * wfr[h][j][0] + cur[j][1] * wfr[h][j][1]) + (cur[j][2] * wfr[h][j][2] + cur[j][3] * wfr[h][j][3]); }
.Lp0b_37:
	s_add_i32 s43, s43, s38
	s_cmpk_gt_i32 s43, 0x7fff
	s_cselect_b64 s[30:31], -1, 0
	s_add_i32 s98, s43, s38
	s_cmpk_gt_i32 s98, 0x7fff
	s_cbranch_scc1 .Lp0b_39
	v_lshl_add_u64 v[250:251], v[184:185], 0, s[28:29]
	global_load_dwordx4 v[144:147], v[250:251], off
	global_load_dwordx4 v[148:151], v[250:251], off offset:1024
	global_load_dwordx4 v[152:155], v[250:251], off offset:2048
	global_load_dwordx4 v[156:159], v[250:251], off offset:3072
.Lp0b_39:
	s_waitcnt lgkmcnt(0)
	v_pk_mul_f32 v[188:189], v[170:171], v[170:171]
	v_pk_mul_f32 v[200:201], v[168:169], v[168:169]
	v_mul_f32_e32 v187, v160, v160
	v_pk_mov_b32 v[202:203], v[200:201], v[188:189] op_sel:[1,0]
	v_mov_b32_e32 v201, v189
	v_pk_add_f32 v[188:189], v[202:203], v[200:201]
	v_pk_mul_f32 v[200:201], v[174:175], v[174:175]
	v_pk_mul_f32 v[202:203], v[172:173], v[172:173]
	v_mul_f32_e32 v199, v161, v161
	v_pk_mov_b32 v[204:205], v[202:203], v[200:201] op_sel:[1,0]
	v_mov_b32_e32 v203, v201
	v_pk_add_f32 v[200:201], v[204:205], v[202:203]
	v_pk_add_f32 v[188:189], v[188:189], v[188:189] op_sel:[0,1] op_sel_hi:[1,0]
	v_pk_add_f32 v[200:201], v[200:201], v[200:201] op_sel:[0,1] op_sel_hi:[1,0]
	v_pk_mul_f32 v[174:175], v[174:175], v[14:15]
	v_pk_mul_f32 v[172:173], v[172:173], v[12:13]
	v_mov_b32_e32 v201, v187
	v_mov_b32_e32 v189, v199
	v_mul_f32_e32 v187, v173, v141
	v_mul_f32_e32 v199, v175, v143
	v_fmac_f32_e32 v187, v172, v140
	v_fmac_f32_e32 v199, v174, v142
	v_mul_f32_e32 v202, v165, v165
	v_mul_f32_e32 v204, v167, v167
	v_pk_add_f32 v[188:189], v[200:201], v[188:189]
	v_add_f32_e32 v187, v187, v199
	v_mul_f32_e32 v199, v173, v125
	v_mul_f32_e32 v200, v175, v127
	v_mul_f32_e32 v206, v162, v162
	v_mul_f32_e32 v207, v163, v163
	v_pk_fma_f32 v[202:203], v[164:165], v[164:165], v[202:203] op_sel_hi:[1,1,0]
	v_pk_fma_f32 v[204:205], v[166:167], v[166:167], v[204:205] op_sel_hi:[1,1,0]
	v_fmac_f32_e32 v199, v172, v124
	v_fmac_f32_e32 v200, v174, v126
	v_mov_b32_e32 v203, v206
	v_mov_b32_e32 v205, v207
	v_add_f32_e32 v199, v199, v200
	v_mul_f32_e32 v200, v173, v109
	v_mul_f32_e32 v201, v175, v111
	v_pk_add_f32 v[202:203], v[202:203], v[204:205]
	v_fmac_f32_e32 v200, v172, v108
	v_fmac_f32_e32 v201, v174, v110
	v_pk_add_f32 v[188:189], v[188:189], v[202:203]
	v_add_f32_e32 v200, v200, v201
	v_mul_f32_e32 v201, v173, v93
	v_mul_f32_e32 v202, v175, v95
	v_fmac_f32_e32 v201, v172, v92
	v_fmac_f32_e32 v202, v174, v94
	v_add_f32_e32 v201, v201, v202
	v_mul_f32_e32 v202, v173, v77
	v_mul_f32_e32 v203, v175, v79
	v_fmac_f32_e32 v202, v172, v76
	v_fmac_f32_e32 v203, v174, v78
	v_add_f32_e32 v202, v202, v203
	v_mul_f32_e32 v203, v173, v61
	v_mul_f32_e32 v204, v175, v63
	v_fmac_f32_e32 v203, v172, v60
	v_fmac_f32_e32 v204, v174, v62
	v_add_f32_e32 v203, v203, v204
	v_mul_f32_e32 v204, v173, v45
	v_mul_f32_e32 v205, v175, v47
	v_fmac_f32_e32 v204, v172, v44
	v_fmac_f32_e32 v205, v174, v46
	v_add_f32_e32 v204, v204, v205
	v_mul_f32_e32 v205, v173, v29
	v_mul_f32_e32 v206, v175, v31
	v_fmac_f32_e32 v205, v172, v28
	v_fmac_f32_e32 v206, v174, v30
	v_pk_mul_f32 v[170:171], v[170:171], v[10:11]
	v_pk_mul_f32 v[168:169], v[168:169], v[8:9]
	v_add_f32_e32 v205, v205, v206
	v_mul_f32_e32 v206, v169, v137
	v_mul_f32_e32 v207, v171, v139
	v_fmac_f32_e32 v206, v168, v136
	v_fmac_f32_e32 v207, v170, v138
	v_add_f32_e32 v187, 0, v187
	v_add_f32_e32 v206, v206, v207
	v_add_f32_e32 v187, v187, v206
	v_mul_f32_e32 v206, v169, v121
	v_mul_f32_e32 v207, v171, v123
	v_fmac_f32_e32 v206, v168, v120
	v_fmac_f32_e32 v207, v170, v122
	v_add_f32_e32 v199, 0, v199
	v_add_f32_e32 v206, v206, v207
	v_add_f32_e32 v199, v199, v206
	v_mul_f32_e32 v206, v169, v105
	v_mul_f32_e32 v207, v171, v107
	v_fmac_f32_e32 v206, v168, v104
	v_fmac_f32_e32 v207, v170, v106
	v_add_f32_e32 v200, 0, v200
	v_add_f32_e32 v206, v206, v207
	v_add_f32_e32 v200, v200, v206
	v_mul_f32_e32 v206, v169, v89
	v_mul_f32_e32 v207, v171, v91
	v_fmac_f32_e32 v206, v168, v88
	v_fmac_f32_e32 v207, v170, v90
	v_add_f32_e32 v201, 0, v201
	v_add_f32_e32 v206, v206, v207
	v_add_f32_e32 v201, v201, v206
	v_mul_f32_e32 v206, v169, v73
	v_mul_f32_e32 v207, v171, v75
	v_fmac_f32_e32 v206, v168, v72
	v_fmac_f32_e32 v207, v170, v74
	v_add_f32_e32 v202, 0, v202
	v_add_f32_e32 v206, v206, v207
	v_add_f32_e32 v202, v202, v206
	v_mul_f32_e32 v206, v169, v57
	v_mul_f32_e32 v207, v171, v59
	v_fmac_f32_e32 v206, v168, v56
	v_fmac_f32_e32 v207, v170, v58
	v_add_f32_e32 v203, 0, v203
	v_add_f32_e32 v206, v206, v207
	v_add_f32_e32 v203, v203, v206
	v_mul_f32_e32 v206, v169, v41
	v_mul_f32_e32 v207, v171, v43
	v_fmac_f32_e32 v206, v168, v40
	v_fmac_f32_e32 v207, v170, v42
	v_add_f32_e32 v204, 0, v204
	v_add_f32_e32 v206, v206, v207
	v_add_f32_e32 v204, v204, v206
	v_mul_f32_e32 v206, v169, v25
	v_mul_f32_e32 v207, v171, v27
	v_fmac_f32_e32 v206, v168, v24
	v_fmac_f32_e32 v207, v170, v26
	v_add_f32_e32 v205, 0, v205
	v_add_f32_e32 v206, v206, v207
	v_pk_mul_f32 v[166:167], v[166:167], v[6:7]
	v_pk_mul_f32 v[164:165], v[164:165], v[4:5]
	v_add_f32_e32 v205, v205, v206
	v_mul_f32_e32 v206, v165, v133
	v_mul_f32_e32 v207, v167, v135
	v_fmac_f32_e32 v206, v164, v132
	v_fmac_f32_e32 v207, v166, v134
	v_add_f32_e32 v206, v206, v207
	v_add_f32_e32 v187, v187, v206
	v_mul_f32_e32 v206, v165, v117
	v_mul_f32_e32 v207, v167, v119
	v_fmac_f32_e32 v206, v164, v116
	v_fmac_f32_e32 v207, v166, v118
	v_add_f32_e32 v206, v206, v207
	v_add_f32_e32 v199, v199, v206
	v_mul_f32_e32 v206, v165, v101
	v_mul_f32_e32 v207, v167, v103
	v_fmac_f32_e32 v206, v164, v100
	v_fmac_f32_e32 v207, v166, v102
	v_add_f32_e32 v206, v206, v207
	v_add_f32_e32 v206, v200, v206
	v_mul_f32_e32 v200, v165, v85
; __device__ __forceinline__ unsigned pk2(float lo, float hi) { return pg8::cvt_pk_bf16(lo, hi); }
; __global__ void __launch_bounds__(NWAVES * 64, 2) mk_fwd(Args args) {
;     ...
;                 for (int j = 0; j < 4; ++j) s += (cur[j][0] * cur[j][0] + cur[j][1] * cur[j][1]) + (cur[j][2] * cur[j][2] + cur[j][3] * cur[j][3]);
;                 float z[8];
; #pragma unroll
;                 for (int h = 0; h < 8; ++h) z[h] = 0.f;
; #pragma unroll
;                 for (int j = 0; j < 4; ++j) { cur[j] = cur[j] * gg[j];
; #pragma unroll
;                     for (int h = 0; h < 8; ++h) z[h] += (cur[j][0] * wfr[h][j][0] + cur[j][1] * wfr[h][j][1]) + (cur[j][2] * wfr[h][j][2] + cur[j][3] * wfr[h][j][3]); }
;                 const float rs = 1.0f / sqrtf(wave_sum(s) * (1.f / DM) + EPS);
;                 unsigned long long* o8 = (unsigned long long*)(XN + (size_t)m * DM) + lane;
; #pragma unroll
;                 for (int j = 0; j < 4; ++j) { const f32x4 v = cur[j] * rs; o8[64 * j] = (unsigned long long)pk2(v[0], v[1]) | ((unsigned long long)pk2(v[2], v[3]) << 32); }
;                 float s4[4], s2[2], s1;
; #pragma unroll
;                 for (int i = 0; i < 4; ++i) { const float send = (lane & 32) ? z[i] : z[4 + i], keep = (lane & 32) ? z[4 + i] : z[i]; s4[i] = keep + __shfl_xor(send, 32); }
; #pragma unroll
;                 for (int i = 0; i < 2; ++i) { const float send = (lane & 16) ? s4[i] : s4[2 + i], keep = (lane & 16) ? s4[2 + i] : s4[i]; s2[i] = keep + __shfl_xor(send, 16); }
;                 { const float send = (lane & 8) ? s2[0] : s2[1], keep = (lane & 8) ? s2[1] : s2[0]; s1 = keep + __shfl_xor(send, 8); }
;                 s1 += __shfl_xor(s1, 4); s1 += __shfl_xor(s1, 2); s1 += __shfl_xor(s1, 1);
	v_mul_f32_e32 v207, v167, v87
	v_fmac_f32_e32 v200, v164, v84
	v_fmac_f32_e32 v207, v166, v86
	v_add_f32_e32 v200, v200, v207
	v_add_f32_e32 v207, v201, v200
	v_mul_f32_e32 v200, v165, v69
	v_mul_f32_e32 v201, v167, v71
	v_fmac_f32_e32 v200, v164, v68
	v_fmac_f32_e32 v201, v166, v70
	v_add_f32_e32 v200, v200, v201
	v_add_f32_e32 v202, v202, v200
	v_mul_f32_e32 v200, v165, v53
	v_mul_f32_e32 v201, v167, v55
	v_fmac_f32_e32 v200, v164, v52
	v_fmac_f32_e32 v201, v166, v54
	v_add_f32_e32 v200, v200, v201
	v_add_f32_e32 v203, v203, v200
	v_mul_f32_e32 v200, v165, v37
	v_mul_f32_e32 v201, v167, v39
	v_fmac_f32_e32 v200, v164, v36
	v_fmac_f32_e32 v201, v166, v38
	v_add_f32_e32 v200, v200, v201
	v_add_f32_e32 v204, v204, v200
	v_mul_f32_e32 v200, v165, v21
	v_mul_f32_e32 v201, v167, v23
	v_fmac_f32_e32 v200, v164, v20
	v_fmac_f32_e32 v201, v166, v22
	v_add_f32_e32 v200, v200, v201
	v_add_f32_e32 v205, v205, v200
	v_pk_mul_f32 v[162:163], v[162:163], v[2:3]
	v_pk_mul_f32 v[200:201], v[160:161], v[0:1]
	v_mul_f32_e32 v161, v163, v131
	v_mul_f32_e32 v160, v201, v129
	v_fmac_f32_e32 v160, v200, v128
	v_fmac_f32_e32 v161, v162, v130
	v_add_f32_e32 v160, v160, v161
	v_add_f32_e32 v161, v187, v160
	v_mul_f32_e32 v160, v201, v113
	v_mul_f32_e32 v187, v163, v115
	v_fmac_f32_e32 v160, v200, v112
	v_fmac_f32_e32 v187, v162, v114
	v_add_f32_e32 v160, v160, v187
	v_add_f32_e32 v187, v199, v160
	v_mul_f32_e32 v160, v201, v97
	v_mul_f32_e32 v199, v163, v99
	v_fmac_f32_e32 v160, v200, v96
	v_fmac_f32_e32 v199, v162, v98
	v_add_f32_e32 v160, v160, v199
	v_add_f32_e32 v199, v206, v160
	v_add_f32_e32 v160, v188, v189
	ds_bpermute_b32 v188, v191, v160
	v_mul_f32_e32 v189, v201, v81
	v_mul_f32_e32 v206, v163, v83
	v_fmac_f32_e32 v189, v200, v80
	v_fmac_f32_e32 v206, v162, v82
	s_waitcnt lgkmcnt(0)
	v_add_f32_e32 v160, v160, v188
	ds_bpermute_b32 v188, v192, v160
	v_add_f32_e32 v189, v189, v206
	v_add_f32_e32 v189, v207, v189
	v_mul_f32_e32 v206, v201, v65
	v_mul_f32_e32 v207, v163, v67
	s_waitcnt lgkmcnt(0)
	v_add_f32_e32 v160, v160, v188
	ds_bpermute_b32 v188, v193, v160
	v_fmac_f32_e32 v206, v200, v64
	v_fmac_f32_e32 v207, v162, v66
	v_add_f32_e32 v206, v206, v207
	v_add_f32_e32 v202, v202, v206
	s_waitcnt lgkmcnt(0)
	v_add_f32_e32 v160, v160, v188
	ds_bpermute_b32 v188, v194, v160
	v_mul_f32_e32 v206, v201, v49
	v_mul_f32_e32 v207, v163, v51
	v_fmac_f32_e32 v206, v200, v48
	v_fmac_f32_e32 v207, v162, v50
	s_waitcnt lgkmcnt(0)
	v_add_f32_e32 v160, v160, v188
	ds_bpermute_b32 v188, v195, v160
	v_add_f32_e32 v206, v206, v207
	v_add_f32_e32 v203, v203, v206
	v_mul_f32_e32 v206, v201, v33
	v_mul_f32_e32 v207, v163, v35
	s_waitcnt lgkmcnt(0)
	v_add_f32_e32 v160, v160, v188
	ds_bpermute_b32 v188, v196, v160
	v_fmac_f32_e32 v206, v200, v32
	v_fmac_f32_e32 v207, v162, v34
	v_add_f32_e32 v206, v206, v207
	v_add_f32_e32 v204, v204, v206
	s_waitcnt lgkmcnt(0)
	v_add_f32_e32 v160, v160, v188
	v_fmamk_f32 v160, v160, 0x3a800000, v177
	v_mul_f32_e32 v188, 0x4f800000, v160
	v_cmp_gt_f32_e32 vcc, s3, v160
	v_mul_f32_e32 v206, v201, v17
	v_mul_f32_e32 v207, v163, v19
	v_cndmask_b32_e32 v160, v160, v188, vcc
	v_sqrt_f32_e32 v188, v160
	v_fmac_f32_e32 v206, v200, v16
	v_fmac_f32_e32 v207, v162, v18
	v_add_f32_e32 v206, v206, v207
	v_add_u32_e32 v208, -1, v188
	v_fma_f32 v209, -v208, v188, v160
	v_cmp_ge_f32_e64 s[12:13], 0, v209
	v_add_u32_e32 v209, 1, v188
	v_add_f32_e32 v205, v205, v206
	v_cndmask_b32_e64 v208, v188, v208, s[12:13]
	v_fma_f32 v188, -v209, v188, v160
	v_cmp_lt_f32_e64 s[12:13], 0, v188
	s_nop 1
	v_cndmask_b32_e64 v188, v208, v209, s[12:13]
	v_mul_f32_e32 v208, 0x37800000, v188
	v_cndmask_b32_e32 v188, v188, v208, vcc
	v_cmp_class_f32_e32 vcc, v160, v179
	s_nop 1
	v_cndmask_b32_e32 v160, v188, v160, vcc
	v_div_scale_f32 v188, s[12:13], v160, v160, 1.0
	v_rcp_f32_e32 v208, v188
	s_nop 0
	v_fma_f32 v206, -v188, v208, 1.0
	v_fmac_f32_e32 v208, v206, v208
	v_div_scale_f32 v206, vcc, 1.0, v160, 1.0
	v_mul_f32_e32 v207, v206, v208
	v_fma_f32 v209, -v188, v207, v206
	v_fmac_f32_e32 v207, v209, v208
	v_fma_f32 v188, -v188, v207, v206
	v_div_fmas_f32 v188, v188, v208, v207
	v_div_fixup_f32 v160, v188, v160, 1.0
	v_cndmask_b32_e64 v188, v161, v202, s[4:5]
	ds_bpermute_b32 v188, v196, v188
	v_pk_mul_f32 v[174:175], v[160:161], v[174:175] op_sel_hi:[0,1]
	v_pk_mul_f32 v[172:173], v[160:161], v[172:173] op_sel_hi:[0,1]
	v_cvt_pk_bf16_f32 v172, v172, v173
	v_cvt_pk_bf16_f32 v173, v174, v175
	v_cndmask_b32_e64 v174, v187, v203, s[4:5]
	v_cndmask_b32_e64 v161, v202, v161, s[4:5]
	v_cndmask_b32_e64 v175, v203, v187, s[4:5]
	ds_bpermute_b32 v174, v196, v174
	v_cndmask_b32_e64 v187, v199, v204, s[4:5]
	s_waitcnt lgkmcnt(1)
	v_add_f32_e32 v161, v161, v188
	ds_bpermute_b32 v187, v196, v187
	v_cndmask_b32_e64 v188, v189, v205, s[4:5]
	ds_bpermute_b32 v188, v196, v188
	s_waitcnt lgkmcnt(2)
	v_add_f32_e32 v174, v175, v174
	v_cndmask_b32_e64 v175, v204, v199, s[4:5]
	s_waitcnt lgkmcnt(1)
	v_add_f32_e32 v175, v175, v187
	v_cndmask_b32_e64 v187, v205, v189, s[4:5]
	s_waitcnt lgkmcnt(0)
	v_add_f32_e32 v187, v187, v188
	v_cndmask_b32_e64 v188, v161, v175, s[6:7]
	v_cndmask_b32_e64 v189, v174, v187, s[6:7]
	ds_bpermute_b32 v188, v195, v188
	ds_bpermute_b32 v189, v195, v189
	global_store_dwordx2 v[182:183], v[172:173], off
	v_cndmask_b32_e64 v161, v175, v161, s[6:7]
	v_cndmask_b32_e64 v172, v187, v174, s[6:7]
	s_waitcnt lgkmcnt(0)
	v_add_f32_e32 v161, v161, v188
	v_add_f32_e32 v172, v172, v189
	v_cndmask_b32_e64 v173, v161, v172, s[8:9]
	ds_bpermute_b32 v173, v194, v173
	v_pk_mul_f32 v[170:171], v[160:161], v[170:171] op_sel_hi:[0,1]
	v_pk_mul_f32 v[168:169], v[160:161], v[168:169] op_sel_hi:[0,1]
	v_cndmask_b32_e64 v161, v172, v161, s[8:9]
	v_cvt_pk_bf16_f32 v168, v168, v169
	s_waitcnt lgkmcnt(0)
	v_add_f32_e32 v161, v161, v173
	ds_bpermute_b32 v172, v193, v161
	v_pk_mul_f32 v[166:167], v[160:161], v[166:167] op_sel_hi:[0,1]
	v_pk_mul_f32 v[164:165], v[160:161], v[164:165] op_sel_hi:[0,1]
	v_cvt_pk_bf16_f32 v169, v170, v171
	global_store_dwordx2 v[182:183], v[168:169], off offset:512
	s_waitcnt lgkmcnt(0)
	v_add_f32_e32 v161, v161, v172
	ds_bpermute_b32 v168, v192, v161
	v_cvt_pk_bf16_f32 v164, v164, v165
	v_cvt_pk_bf16_f32 v165, v166, v167
	global_store_dwordx2 v[182:183], v[164:165], off offset:1024
	v_pk_mul_f32 v[164:165], v[160:161], v[162:163] op_sel_hi:[0,1]
	s_waitcnt lgkmcnt(0)
	v_add_f32_e32 v161, v161, v168
	ds_bpermute_b32 v162, v191, v161
	v_pk_mul_f32 v[166:167], v[160:161], v[200:201] op_sel_hi:[0,1]
	v_cvt_pk_bf16_f32 v166, v166, v167
	v_cvt_pk_bf16_f32 v167, v164, v165
	global_store_dwordx2 v[182:183], v[166:167], off offset:1536
	s_cmpk_gt_i32 s98, 0x7fff
	s_cbranch_scc1 .Lp0w4_2
	s_waitcnt vmcnt(8)
	s_branch .Lp0wd_2

; __global__ void __launch_bounds__(NWAVES * 64, 2) mk_fwd(Args args) {
;     ...
;             for (; m < T; m += NGW) {
;                 const int mn = m + NGW;
;                 if (mn < T) { const f32x4* xr = (const f32x4*)(x + (size_t)mn * DM) + lane;
; #pragma unroll
;                     for (int j = 0; j < 4; ++j) nxt[j] = xr[64 * j]; }
;     ...
;                 if ((lane & 7) == 0) { const float zz = s1 * rs + bfl; LOGF[(size_t)m * 8 + hsel] = fminf(zz, 0.f) - log1pf(expf(-fabsf(zz))); }
; #pragma unroll
;                 for (int j = 0; j < 4; ++j) cur[j] = nxt[j];
;             }
.Lp0wd_2:
	s_and_saveexec_b64 s[12:13], s[10:11]
	s_cbranch_execz .Lp0b_36
	s_waitcnt lgkmcnt(0)
	v_add_f32_e32 v161, v161, v162
	v_fma_f32 v160, v160, v161, v190
	v_mul_f32_e64 v161, |v160|, s15
	v_fma_f32 v162, |v160|, s15, -v161
	v_rndne_f32_e32 v163, v161
	v_fma_f32 v162, |v160|, s33, v162
	v_sub_f32_e32 v161, v161, v163
	v_add_f32_e32 v161, v161, v162
	v_exp_f32_e32 v161, v161
	v_cvt_i32_f32_e32 v162, v163
	v_cmp_ngt_f32_e64 vcc, |v160|, s34
	v_min_f32_e32 v174, 0, v160
	v_ldexp_f32 v161, v161, v162
	v_cndmask_b32_e32 v161, 0, v161, vcc
	v_cmp_nlt_f32_e64 vcc, |v160|, s35
	s_nop 1
	v_cndmask_b32_e32 v175, v198, v161, vcc
	v_add_f32_e32 v162, 1.0, v175
	v_add_f32_e32 v160, -1.0, v162
	v_sub_f32_e32 v161, v160, v162
	v_add_f32_e32 v161, 1.0, v161
	v_sub_f32_e32 v160, v175, v160
	v_add_f32_e32 v163, v160, v161
	v_frexp_mant_f32_e32 v164, v162
	v_cvt_f64_f32_e32 v[160:161], v162
	v_frexp_exp_i32_f64_e32 v160, v[160:161]
	v_cmp_gt_f32_e32 vcc, s37, v164
	s_nop 1
	v_subbrev_co_u32_e32 v168, vcc, 0, v160, vcc
	v_sub_u32_e32 v160, 0, v168
	v_ldexp_f32 v161, v162, v160
	v_add_f32_e32 v162, -1.0, v161
	v_add_f32_e32 v164, 1.0, v161
	v_ldexp_f32 v160, v163, v160
	v_add_f32_e32 v163, 1.0, v162
	v_add_f32_e32 v165, -1.0, v164
	v_sub_f32_e32 v163, v161, v163
	v_sub_f32_e32 v161, v161, v165
	v_add_f32_e32 v163, v160, v163
	v_add_f32_e32 v160, v160, v161
	v_add_f32_e32 v169, v164, v160
	v_rcp_f32_e32 v171, v169
	v_sub_f32_e32 v161, v164, v169
	v_add_f32_e32 v170, v160, v161
	v_add_f32_e32 v161, v162, v163
	v_mul_f32_e32 v173, v161, v171
	v_sub_f32_e32 v160, v162, v161
	v_mul_f32_e32 v162, v169, v173
	v_fma_f32 v164, v173, v169, -v162
	v_fmac_f32_e32 v164, v173, v170
	v_add_f32_e32 v172, v163, v160
	v_add_f32_e32 v160, v162, v164
	v_sub_f32_e32 v163, v161, v160
	v_pk_add_f32 v[166:167], v[160:161], v[162:163] neg_lo:[0,1] neg_hi:[0,1]
	v_mov_b32_e32 v165, v160
	v_pk_add_f32 v[160:161], v[166:167], v[164:165] neg_lo:[0,1] neg_hi:[0,1]
	v_cmp_neq_f32_e32 vcc, s36, v175
	v_add_f32_e32 v161, v172, v161
	v_add_f32_e32 v160, v160, v161
	v_add_f32_e32 v161, v163, v160
	v_mul_f32_e32 v172, v171, v161
	v_mul_f32_e32 v162, v169, v172
	v_fma_f32 v164, v172, v169, -v162
	v_fmac_f32_e32 v164, v172, v170
	v_sub_f32_e32 v163, v163, v161
	v_add_f32_e32 v169, v160, v163
	v_add_f32_e32 v160, v162, v164
	v_sub_f32_e32 v163, v161, v160
	v_pk_add_f32 v[166:167], v[160:161], v[162:163] neg_lo:[0,1] neg_hi:[0,1]
	v_mov_b32_e32 v165, v160
	v_pk_add_f32 v[160:161], v[166:167], v[164:165] neg_lo:[0,1] neg_hi:[0,1]
	s_nop 0
	v_add_f32_e32 v161, v169, v161
	v_add_f32_e32 v160, v160, v161
	v_add_f32_e32 v161, v173, v172
	v_add_f32_e32 v160, v163, v160
	v_sub_f32_e32 v162, v161, v173
	v_mul_f32_e32 v160, v171, v160
	v_sub_f32_e32 v162, v172, v162
	v_add_f32_e32 v162, v162, v160
	v_add_f32_e32 v164, v161, v162
	v_mul_f32_e32 v165, v164, v164
	v_fmamk_f32 v160, v165, 0x3e9b6dac, v197
	v_fmaak_f32 v187, v165, v160, 0x3f2aaada
	v_cvt_f32_i32_e32 v160, v168
	v_sub_f32_e32 v161, v164, v161
	v_sub_f32_e32 v161, v162, v161
	v_ldexp_f32 v166, v161, 1
	v_mul_f32_e32 v161, v164, v165
	v_ldexp_f32 v163, v164, 1
	v_pk_mul_f32 v[164:165], v[160:161], v[186:187]
	s_nop 0
	v_fma_f32 v162, v160, s39, -v164
	v_fmac_f32_e32 v162, 0xb102e308, v160
	v_pk_add_f32 v[160:161], v[164:165], v[162:163]
	s_nop 0
	v_sub_f32_e32 v163, v161, v163
	v_sub_f32_e32 v163, v165, v163
	v_add_f32_e32 v167, v166, v163
	v_mov_b32_e32 v166, v164
	v_pk_add_f32 v[164:165], v[160:161], v[164:165] neg_lo:[0,1] neg_hi:[0,1]
	v_pk_add_f32 v[168:169], v[160:161], v[166:167]
	v_mov_b32_e32 v163, v160
	v_mov_b32_e32 v165, v169
	v_pk_add_f32 v[170:171], v[162:163], v[164:165] neg_lo:[0,1] neg_hi:[0,1]
	v_pk_add_f32 v[162:163], v[162:163], v[164:165]
	v_mov_b32_e32 v166, v167
	v_pk_add_f32 v[164:165], v[162:163], v[160:161] op_sel:[1,0] op_sel_hi:[0,1] neg_lo:[0,1] neg_hi:[0,1]
	v_pk_add_f32 v[172:173], v[168:169], v[164:165] op_sel_hi:[1,0] neg_lo:[0,1] neg_hi:[0,1]
	v_mov_b32_e32 v168, v169
	v_mov_b32_e32 v169, v163
	v_pk_mov_b32 v[164:165], v[160:161], v[164:165] op_sel:[1,0]
	v_mov_b32_e32 v167, v160
	v_pk_add_f32 v[164:165], v[168:169], v[164:165] neg_lo:[0,1] neg_hi:[0,1]
	v_mov_b32_e32 v172, v170
	v_pk_add_f32 v[160:161], v[166:167], v[164:165] neg_lo:[0,1] neg_hi:[0,1]
	v_mov_b32_e32 v171, v163
	v_pk_add_f32 v[164:165], v[172:173], v[160:161]
	s_nop 0
	v_pk_add_f32 v[166:167], v[164:165], v[164:165] op_sel:[0,1] op_sel_hi:[1,0]
	s_nop 0
	v_pk_add_f32 v[162:163], v[162:163], v[166:167] op_sel:[1,0] op_sel_hi:[0,1]
	v_mov_b32_e32 v165, v162
	v_pk_add_f32 v[168:169], v[164:165], v[170:171] neg_lo:[0,1] neg_hi:[0,1]
	v_mov_b32_e32 v161, v166
	v_sub_f32_e32 v163, v164, v168
	v_pk_add_f32 v[160:161], v[160:161], v[168:169] neg_lo:[0,1] neg_hi:[0,1]
	v_sub_f32_e32 v163, v170, v163
	v_add_f32_e32 v160, v160, v163
	v_add_f32_e32 v160, v160, v161
	v_add_f32_e32 v160, v162, v160
	v_cndmask_b32_e32 v160, v198, v160, vcc
	v_cmp_lt_f32_e64 vcc, |v175|, s42
	s_nop 1
	v_cndmask_b32_e32 v160, v160, v175, vcc
	v_sub_f32_e32 v160, v174, v160
	global_store_dword v[180:181], v160, off
	s_branch .Lp0b_36
.Lp0b_36:
	s_or_b64 exec, exec, s[12:13]
	v_mov_b64_e32 v[174:175], v[236:237]
	v_mov_b64_e32 v[170:171], v[240:241]
	v_mov_b64_e32 v[166:167], v[244:245]
	s_waitcnt lgkmcnt(0)
	v_mov_b64_e32 v[162:163], v[248:249]
	v_lshl_add_u64 v[180:181], v[180:181], 0, s[26:27]
	v_lshl_add_u64 v[182:183], v[182:183], 0, s[22:23]
	v_lshl_add_u64 v[184:185], v[184:185], 0, s[28:29]
	s_andn2_b64 vcc, exec, s[30:31]
	v_mov_b64_e32 v[172:173], v[234:235]
	v_mov_b64_e32 v[168:169], v[238:239]
	v_mov_b64_e32 v[164:165], v[242:243]
	v_mov_b64_e32 v[160:161], v[246:247]
	s_cbranch_vccz .LBB0_41
.LBB0_37:
	s_add_i32 s43, s43, s38
	s_cmpk_gt_i32 s43, 0x7fff
	s_cselect_b64 s[30:31], -1, 0
	s_add_i32 s98, s43, s38
	s_cmpk_gt_i32 s98, 0x7fff
	s_cbranch_scc1 .LBB0_39
	v_lshl_add_u64 v[250:251], v[184:185], 0, s[28:29]
	global_load_dwordx4 v[234:237], v[250:251], off
	global_load_dwordx4 v[238:241], v[250:251], off offset:1024
	global_load_dwordx4 v[242:245], v[250:251], off offset:2048
	global_load_dwordx4 v[246:249], v[250:251], off offset:3072
